# attention: half-block stagger of waves 4-7 (barrier between Q.K and P.V half-steps) on top of K-DMA-after-barrier
# speedup vs baseline: 1.0001x; 1.0001x over previous
; #define WAIT_BAR(N) asm volatile("s_waitcnt vmcnt(" #N ") lgkmcnt(0)\n\ts_barrier":::"memory")
;   #define RESC() do{}while(0)
;   #define ROT() do{sl_prev=sl_cur;sl_cur=sl_next;sl_next=(sl_next==(NSLOT-1)*SLOTB)?0:sl_next+SLOTB;}while(0)
; template<int THRL> __device__ __forceinline__ void attn_unit(int b,int h,int qb,const bf16*Q,const bf16*__restrict__ K,const bf16*__restrict__ V,bf16*O,char*shm,float m2){
;     ...
;   int t=1;
;   for(;t+5<NT;t+=2){
;     STEP(pB0,pB1,pA0,pA1,t,true,true,true);     WAIT_BAR(2); RESC(); ROT();
.LBB0_829:
	v_add_u32_e32 v190, s17, v220
	ds_read_b64_tr_b16 v[230:231], v190 offset:24576
	ds_read_b64_tr_b16 v[232:233], v190 offset:25088
	s_waitcnt lgkmcnt(9)
	v_mfma_f32_32x32x16_bf16 v[114:129], v[98:101], v[174:177], v[50:65]
	v_exp_f32_e32 v78, v78
	v_add_f32_e32 v102, v82, v83
	v_add_f32_e32 v102, v84, v102
	v_add_f32_e32 v102, v85, v102
	v_add_f32_e32 v102, v86, v102
	v_add_f32_e32 v102, v87, v102
	v_cvt_pk_bf16_f32 v166, v82, v83
	v_cvt_pk_bf16_f32 v167, v84, v85
	ds_read_b64_tr_b16 v[82:83], v190 offset:28672
	ds_read_b64_tr_b16 v[84:85], v190 offset:29184
	v_add_f32_e32 v98, v88, v102
	v_add_f32_e32 v98, v89, v98
	v_add_f32_e32 v98, v90, v98
	v_add_f32_e32 v146, v91, v98
	s_waitcnt lgkmcnt(10)
	v_mfma_f32_32x32x16_bf16 v[98:113], v[182:185], v[174:177], v[50:65]
	v_exp_f32_e32 v79, v79
	v_cvt_pk_bf16_f32 v168, v86, v87
	v_cvt_pk_bf16_f32 v169, v88, v89
	ds_read_b64_tr_b16 v[86:87], v190 offset:25600
	ds_read_b64_tr_b16 v[88:89], v190 offset:26112
	v_add_f32_e32 v146, v92, v146
	v_add_f32_e32 v146, v93, v146
	v_add_f32_e32 v146, v94, v146
	v_add_f32_e32 v146, v95, v146
	v_cvt_pk_bf16_f32 v158, v90, v91
	v_cvt_pk_bf16_f32 v159, v92, v93
	s_waitcnt lgkmcnt(11)
	v_mfma_f32_32x32x16_bf16 v[114:129], v[186:189], v[170:173], v[114:129]
	v_exp_f32_e32 v80, v80
	ds_read_b64_tr_b16 v[90:91], v190 offset:29696
	ds_read_b64_tr_b16 v[92:93], v190 offset:30208
	s_waitcnt lgkmcnt(12)
	v_mfma_f32_32x32x16_bf16 v[98:113], v[178:181], v[170:173], v[98:113]
	v_exp_f32_e32 v81, v81
	v_add_f32_e32 v146, v96, v146
	v_add_f32_e32 v146, v97, v146
	v_add_f32_e32 v146, v66, v146
	v_add_f32_e32 v146, v67, v146
	v_cvt_pk_bf16_f32 v160, v94, v95
	v_cvt_pk_bf16_f32 v161, v96, v97
	ds_read_b64_tr_b16 v[94:95], v190 offset:26624
	ds_read_b64_tr_b16 v[96:97], v190 offset:27136
	s_waitcnt lgkmcnt(13)
	v_mfma_f32_32x32x16_bf16 v[114:129], v[142:145], v[162:165], v[114:129]
	v_add_f32_e32 v142, v68, v146
	v_add_f32_e32 v142, v69, v142
	v_add_f32_e32 v142, v70, v142
	v_add_f32_e32 v142, v71, v142
	v_cvt_pk_bf16_f32 v150, v66, v67
	v_cvt_pk_bf16_f32 v151, v68, v69
	ds_read_b64_tr_b16 v[66:67], v190 offset:30720
	ds_read_b64_tr_b16 v[68:69], v190 offset:31232
	s_waitcnt lgkmcnt(14)
	v_mfma_f32_32x32x16_bf16 v[98:113], v[138:141], v[162:165], v[98:113]
	v_add_f32_e32 v138, v72, v142
	v_add_f32_e32 v138, v73, v138
	v_add_f32_e32 v138, v74, v138
	v_add_f32_e32 v138, v75, v138
	v_cvt_pk_bf16_f32 v152, v70, v71
	v_cvt_pk_bf16_f32 v153, v72, v73
	ds_read_b64_tr_b16 v[70:71], v190 offset:27648
	ds_read_b64_tr_b16 v[72:73], v190 offset:28160
	s_waitcnt lgkmcnt(14)
	v_mfma_f32_32x32x16_bf16 v[114:129], v[134:137], v[154:157], v[114:129]
	v_add_f32_e32 v134, v76, v138
	v_add_f32_e32 v134, v77, v134
	v_add_f32_e32 v134, v78, v134
	v_add_f32_e32 v134, v79, v134
	v_cvt_pk_bf16_f32 v146, v74, v75
	v_cvt_pk_bf16_f32 v147, v76, v77
	ds_read_b64_tr_b16 v[74:75], v190 offset:31744
	ds_read_b64_tr_b16 v[76:77], v190 offset:32256
	v_mfma_f32_32x32x16_bf16 v[98:113], v[130:133], v[154:157], v[98:113]
	v_add_f32_e32 v130, v80, v134
	v_add_f32_e32 v130, v81, v130
	v_add_f32_e32 v130, 0, v130
	v_cvt_pk_bf16_f32 v148, v78, v79
	v_cvt_pk_bf16_f32 v149, v80, v81
	v_lshl_add_u64 v[78:79], v[216:217], 0, s[42:43]
	s_add_i32 s0, s15, s4
	s_mov_b32 s17, m0
	s_mov_b32 m0, s0
	s_nop 0
	global_load_lds_dwordx4 v[78:79], off
	s_mov_b32 m0, s17
	s_cmpk_lt_u32 s13, 0x100
	s_cbranch_scc1 .Lstg_a1
	s_waitcnt vmcnt(1) lgkmcnt(0)
	s_barrier
	v_lshl_add_u64 v[238:239], v[214:215], 0, s[48:49]
	s_add_i32 s98, s16, s12
	s_mov_b32 s99, m0
	s_mov_b32 m0, s98
	s_nop 0
	global_load_lds_dwordx4 v[238:239], off
	s_mov_b32 m0, s99
.Lstg_a1:
	v_add_f32_e32 v190, v199, v130
	s_waitcnt lgkmcnt(14)
	v_mfma_f32_32x32x16_bf16 v[18:33], v[166:169], v[230:233], v[18:33]
	v_exp_f32_e32 v114, v114
	v_exp_f32_e32 v115, v115
	v_exp_f32_e32 v116, v116
	v_exp_f32_e32 v117, v117
	s_waitcnt lgkmcnt(12)
	v_mfma_f32_32x32x16_bf16 v[34:49], v[166:169], v[82:85], v[34:49]
	v_exp_f32_e32 v118, v118
	v_exp_f32_e32 v119, v119
	v_exp_f32_e32 v120, v120
	v_exp_f32_e32 v121, v121
	v_add_u32_e32 v82, s15, v219
	ds_read_b128 v[78:81], v82
	ds_read_b128 v[134:137], v82 offset:512
	s_waitcnt lgkmcnt(12)
	v_mfma_f32_32x32x16_bf16 v[18:33], v[158:161], v[86:89], v[18:33]
	v_exp_f32_e32 v122, v122
	v_exp_f32_e32 v123, v123
	v_exp_f32_e32 v124, v124
	v_exp_f32_e32 v125, v125
	ds_read_b128 v[138:141], v82 offset:2048
	ds_read_b128 v[142:145], v82 offset:2560
	s_waitcnt lgkmcnt(12)
	v_mfma_f32_32x32x16_bf16 v[34:49], v[158:161], v[90:93], v[34:49]
	v_exp_f32_e32 v126, v126
	v_exp_f32_e32 v127, v127
	v_exp_f32_e32 v128, v128
	v_exp_f32_e32 v129, v129
	ds_read_b128 v[178:181], v82 offset:4096
	ds_read_b128 v[182:185], v82 offset:4608
	s_waitcnt lgkmcnt(12)
	v_mfma_f32_32x32x16_bf16 v[18:33], v[150:153], v[94:97], v[18:33]
	v_exp_f32_e32 v98, v98
	v_exp_f32_e32 v99, v99
	v_exp_f32_e32 v100, v100
	v_exp_f32_e32 v101, v101
	ds_read_b128 v[186:189], v82 offset:6144
	ds_read_b128 v[130:133], v82 offset:6656
	s_waitcnt lgkmcnt(12)
	v_mfma_f32_32x32x16_bf16 v[34:49], v[150:153], v[66:69], v[34:49]
	v_exp_f32_e32 v102, v102
	v_exp_f32_e32 v103, v103
	v_exp_f32_e32 v104, v104
	v_exp_f32_e32 v105, v105
	s_waitcnt lgkmcnt(10)
	v_mfma_f32_32x32x16_bf16 v[18:33], v[146:149], v[70:73], v[18:33]
	v_exp_f32_e32 v106, v106
	v_exp_f32_e32 v107, v107
	v_exp_f32_e32 v108, v108
	v_exp_f32_e32 v109, v109
	s_waitcnt lgkmcnt(8)
	v_mfma_f32_32x32x16_bf16 v[34:49], v[146:149], v[74:77], v[34:49]
	s_cmpk_lt_u32 s13, 0x100
	s_cbranch_scc0 .Lstg_b1
	s_waitcnt vmcnt(1) lgkmcnt(0)
	s_barrier
	v_lshl_add_u64 v[238:239], v[214:215], 0, s[48:49]
	s_add_i32 s98, s16, s12
	s_mov_b32 s99, m0
	s_mov_b32 m0, s98
	s_nop 0
	global_load_lds_dwordx4 v[238:239], off
	s_mov_b32 m0, s99
; #define WAIT_BAR(N) asm volatile("s_waitcnt vmcnt(" #N ") lgkmcnt(0)\n\ts_barrier":::"memory")
;   #define RESC() do{}while(0)
;   #define ROT() do{sl_prev=sl_cur;sl_cur=sl_next;sl_next=(sl_next==(NSLOT-1)*SLOTB)?0:sl_next+SLOTB;}while(0)
; template<int THRL> __device__ __forceinline__ void attn_unit(int b,int h,int qb,const bf16*Q,const bf16*__restrict__ K,const bf16*__restrict__ V,bf16*O,char*shm,float m2){
;     ...
;   int t=1;
;   for(;t+5<NT;t+=2){
;     STEP(pB0,pB1,pA0,pA1,t,true,true,true);     WAIT_BAR(2); RESC(); ROT();
;     STEP(pA0,pA1,pB0,pB1,t+1,true,true,true);   WAIT_BAR(2); RESC(); ROT();
.Lstg_b1:
	s_add_i32 s0, s15, 0x2000
	s_cmpk_lg_i32 s15, 0x4000
	s_cselect_b32 s0, s0, 0
	v_add_u32_e32 v199, s16, v220
	ds_read_b64_tr_b16 v[230:231], v199 offset:24576
	ds_read_b64_tr_b16 v[232:233], v199 offset:25088
	s_waitcnt lgkmcnt(9)
	v_mfma_f32_32x32x16_bf16 v[82:97], v[78:81], v[174:177], v[50:65]
	v_exp_f32_e32 v110, v110
	v_add_f32_e32 v66, v114, v115
	v_add_f32_e32 v66, v116, v66
	v_add_f32_e32 v66, v117, v66
	v_add_f32_e32 v66, v118, v66
	v_add_f32_e32 v66, v119, v66
	v_cvt_pk_bf16_f32 v166, v114, v115
	v_cvt_pk_bf16_f32 v167, v116, v117
	ds_read_b64_tr_b16 v[114:115], v199 offset:28672
	ds_read_b64_tr_b16 v[116:117], v199 offset:29184
	v_add_f32_e32 v66, v120, v66
	v_add_f32_e32 v66, v121, v66
	v_add_f32_e32 v66, v122, v66
	v_add_f32_e32 v146, v123, v66
	s_waitcnt lgkmcnt(10)
	v_mfma_f32_32x32x16_bf16 v[66:81], v[134:137], v[174:177], v[50:65]
	v_exp_f32_e32 v111, v111
	v_cvt_pk_bf16_f32 v168, v118, v119
	v_cvt_pk_bf16_f32 v169, v120, v121
	ds_read_b64_tr_b16 v[118:119], v199 offset:25600
	ds_read_b64_tr_b16 v[120:121], v199 offset:26112
	s_waitcnt lgkmcnt(11)
	v_mfma_f32_32x32x16_bf16 v[82:97], v[138:141], v[170:173], v[82:97]
	v_exp_f32_e32 v112, v112
	v_add_f32_e32 v134, v124, v146
	v_add_f32_e32 v134, v125, v134
	v_add_f32_e32 v134, v126, v134
	v_add_f32_e32 v134, v127, v134
	v_cvt_pk_bf16_f32 v158, v122, v123
	v_cvt_pk_bf16_f32 v159, v124, v125
	ds_read_b64_tr_b16 v[122:123], v199 offset:29696
	ds_read_b64_tr_b16 v[124:125], v199 offset:30208
	s_waitcnt lgkmcnt(12)
	v_mfma_f32_32x32x16_bf16 v[66:81], v[142:145], v[170:173], v[66:81]
	v_exp_f32_e32 v113, v113
	v_add_f32_e32 v134, v128, v134
	v_add_f32_e32 v134, v129, v134
	v_add_f32_e32 v134, v98, v134
	v_add_f32_e32 v134, v99, v134
	v_cvt_pk_bf16_f32 v160, v126, v127
	v_cvt_pk_bf16_f32 v161, v128, v129
	ds_read_b64_tr_b16 v[126:127], v199 offset:26624
	ds_read_b64_tr_b16 v[128:129], v199 offset:27136
	s_waitcnt lgkmcnt(13)
	v_mfma_f32_32x32x16_bf16 v[82:97], v[178:181], v[162:165], v[82:97]
	v_add_f32_e32 v134, v100, v134
	v_add_f32_e32 v134, v101, v134
	v_add_f32_e32 v134, v102, v134
	v_add_f32_e32 v134, v103, v134
	v_cvt_pk_bf16_f32 v150, v98, v99
	v_cvt_pk_bf16_f32 v151, v100, v101
	ds_read_b64_tr_b16 v[234:235], v199 offset:30720
	ds_read_b64_tr_b16 v[236:237], v199 offset:31232
	s_waitcnt lgkmcnt(14)
	v_mfma_f32_32x32x16_bf16 v[66:81], v[182:185], v[162:165], v[66:81]
	v_add_f32_e32 v98, v104, v134
	v_add_f32_e32 v98, v105, v98
	v_add_f32_e32 v98, v106, v98
	v_add_f32_e32 v98, v107, v98
	v_cvt_pk_bf16_f32 v152, v102, v103
	v_cvt_pk_bf16_f32 v153, v104, v105
	ds_read_b64_tr_b16 v[102:103], v199 offset:27648
	ds_read_b64_tr_b16 v[104:105], v199 offset:28160
	s_waitcnt lgkmcnt(14)
	v_mfma_f32_32x32x16_bf16 v[82:97], v[186:189], v[154:157], v[82:97]
	v_add_f32_e32 v98, v108, v98
	v_add_f32_e32 v98, v109, v98
	v_add_f32_e32 v98, v110, v98
	v_add_f32_e32 v98, v111, v98
	v_cvt_pk_bf16_f32 v146, v106, v107
	v_cvt_pk_bf16_f32 v147, v108, v109
	ds_read_b64_tr_b16 v[106:107], v199 offset:31744
	ds_read_b64_tr_b16 v[108:109], v199 offset:32256
	v_mfma_f32_32x32x16_bf16 v[66:81], v[130:133], v[154:157], v[66:81]
	v_add_f32_e32 v98, v112, v98
	v_add_f32_e32 v98, v113, v98
	v_add_f32_e32 v98, 0, v98
	v_cvt_pk_bf16_f32 v148, v110, v111
	v_cvt_pk_bf16_f32 v149, v112, v113
	v_add_f32_e32 v199, v190, v98
	v_lshl_add_u64 v[216:217], v[216:217], 0, s[46:47]
	s_add_i32 s16, s0, s4
	s_mov_b32 s17, m0
	s_mov_b32 m0, s16
	s_nop 0
	global_load_lds_dwordx4 v[216:217], off
	s_mov_b32 m0, s17
	s_cmpk_lt_u32 s13, 0x100
	s_cbranch_scc1 .Lstg_a2
	s_waitcnt vmcnt(1) lgkmcnt(0)
	s_barrier
	s_mov_b64 s[100:101], 0x10000
	v_lshl_add_u64 v[238:239], v[214:215], 0, s[100:101]
	s_add_i32 s98, s15, s12
	s_mov_b32 s99, m0
	s_mov_b32 m0, s98
	s_nop 0
	global_load_lds_dwordx4 v[238:239], off
	s_mov_b32 m0, s99
.Lstg_a2:
	s_waitcnt lgkmcnt(14)
	v_mfma_f32_32x32x16_bf16 v[18:33], v[166:169], v[230:233], v[18:33]
	v_exp_f32_e32 v82, v82
	v_exp_f32_e32 v83, v83
	v_exp_f32_e32 v84, v84
	v_exp_f32_e32 v85, v85
	s_waitcnt lgkmcnt(12)
	v_mfma_f32_32x32x16_bf16 v[34:49], v[166:169], v[114:117], v[34:49]
	v_exp_f32_e32 v86, v86
	v_exp_f32_e32 v87, v87
	v_exp_f32_e32 v88, v88
	v_exp_f32_e32 v89, v89
	v_add_u32_e32 v110, s0, v219
	ds_read_b128 v[98:101], v110
	ds_read_b128 v[182:185], v110 offset:512
	s_waitcnt lgkmcnt(12)
	v_mfma_f32_32x32x16_bf16 v[18:33], v[158:161], v[118:121], v[18:33]
	v_exp_f32_e32 v90, v90
	v_exp_f32_e32 v91, v91
	v_exp_f32_e32 v92, v92
	v_exp_f32_e32 v93, v93
	ds_read_b128 v[186:189], v110 offset:2048
	ds_read_b128 v[178:181], v110 offset:2560
	s_waitcnt lgkmcnt(12)
	v_mfma_f32_32x32x16_bf16 v[34:49], v[158:161], v[122:125], v[34:49]
	v_exp_f32_e32 v94, v94
	v_exp_f32_e32 v95, v95
	v_exp_f32_e32 v96, v96
	v_exp_f32_e32 v97, v97
	ds_read_b128 v[142:145], v110 offset:4096
	ds_read_b128 v[138:141], v110 offset:4608
	s_waitcnt lgkmcnt(12)
	v_mfma_f32_32x32x16_bf16 v[18:33], v[150:153], v[126:129], v[18:33]
	v_exp_f32_e32 v66, v66
	v_exp_f32_e32 v67, v67
	v_exp_f32_e32 v68, v68
	v_exp_f32_e32 v69, v69
	ds_read_b128 v[134:137], v110 offset:6144
	ds_read_b128 v[130:133], v110 offset:6656
	s_waitcnt lgkmcnt(12)
	v_mfma_f32_32x32x16_bf16 v[34:49], v[150:153], v[234:237], v[34:49]
	v_exp_f32_e32 v70, v70
	v_exp_f32_e32 v71, v71
	v_exp_f32_e32 v72, v72
	v_exp_f32_e32 v73, v73
	s_waitcnt lgkmcnt(10)
	v_mfma_f32_32x32x16_bf16 v[18:33], v[146:149], v[102:105], v[18:33]
	v_exp_f32_e32 v74, v74
	v_exp_f32_e32 v75, v75
	v_exp_f32_e32 v76, v76
	v_exp_f32_e32 v77, v77
	s_waitcnt lgkmcnt(8)
	v_mfma_f32_32x32x16_bf16 v[34:49], v[146:149], v[106:109], v[34:49]
	s_add_i32 s18, s0, 0x2000
	s_cmpk_lt_u32 s13, 0x100
	s_cbranch_scc0 .Lstg_b2
	s_waitcnt vmcnt(1) lgkmcnt(0)
	s_barrier
	s_mov_b64 s[100:101], 0x10000
	v_lshl_add_u64 v[238:239], v[214:215], 0, s[100:101]
	s_add_i32 s98, s15, s12
	s_mov_b32 s99, m0
	s_mov_b32 m0, s98
	s_nop 0
	global_load_lds_dwordx4 v[238:239], off
	s_mov_b32 m0, s99
; #define WAIT_BAR(N) asm volatile("s_waitcnt vmcnt(" #N ") lgkmcnt(0)\n\ts_barrier":::"memory")
;   #define RESC() do{}while(0)
;   #define ROT() do{sl_prev=sl_cur;sl_cur=sl_next;sl_next=(sl_next==(NSLOT-1)*SLOTB)?0:sl_next+SLOTB;}while(0)
;   #define ENDW(tt) do{ if((tt)+3<NT){WAIT_BAR(2);} else if((tt)+2<NT){WAIT_BAR(1);} else {WAIT_BAR(0);} }while(0)
; template<int THRL> __device__ __forceinline__ void attn_unit(int b,int h,int qb,const bf16*Q,const bf16*__restrict__ K,const bf16*__restrict__ V,bf16*O,char*shm,float m2){
;     ...
;   int t=1;
;   for(;t+5<NT;t+=2){
;     STEP(pB0,pB1,pA0,pA1,t,true,true,true);     WAIT_BAR(2); RESC(); ROT();
;     STEP(pA0,pA1,pB0,pB1,t+1,true,true,true);   WAIT_BAR(2); RESC(); ROT();
;   }
;     ...
;   for(;t+1<NT;t+=2){
;     STEP(pB0,pB1,pA0,pA1,t,(t+3<NT),(t+1<NT),(t+1<NT));       ENDW(t);   RESC(); ROT();
.Lstg_b2:
	s_cmpk_lg_i32 s0, 0x4000
	s_mov_b32 s17, s15
	s_cselect_b32 s15, s18, 0
	s_add_i32 s14, s14, 2
	v_lshl_add_u64 v[214:215], v[214:215], 0, s[46:47]
	s_mov_b32 s16, s0
	s_cmpk_gt_u32 s14, 0x78
	s_cbranch_scc0 .LBB0_829
	v_exp_f32_e32 v78, v78
	v_exp_f32_e32 v79, v79
	v_exp_f32_e32 v80, v80
	v_exp_f32_e32 v81, v81
	s_and_b32 s0, s13, 0x3fffffc0
	s_lshl_b32 s0, s0, 2
	s_add_i32 s0, s0, 0
	ds_read_b64_tr_b16 v[214:215], v220 offset:40960
	ds_read_b64_tr_b16 v[216:217], v220 offset:41472
	v_add_f32_e32 v102, v82, v83
	v_add_f32_e32 v102, v84, v102
	v_add_f32_e32 v102, v85, v102
	v_add_f32_e32 v102, v86, v102
	v_add_f32_e32 v102, v87, v102
	v_cvt_pk_bf16_f32 v166, v82, v83
	v_cvt_pk_bf16_f32 v167, v84, v85
	s_waitcnt lgkmcnt(9)
	v_mfma_f32_32x32x16_bf16 v[114:129], v[98:101], v[174:177], v[50:65]
	ds_read_b64_tr_b16 v[82:83], v220 offset:45056
	ds_read_b64_tr_b16 v[84:85], v220 offset:45568
	v_add_f32_e32 v98, v88, v102
	v_add_f32_e32 v98, v89, v98
	v_add_f32_e32 v98, v90, v98
	v_add_f32_e32 v146, v91, v98
	v_cvt_pk_bf16_f32 v168, v86, v87
	v_cvt_pk_bf16_f32 v169, v88, v89
	s_waitcnt lgkmcnt(10)
	v_mfma_f32_32x32x16_bf16 v[98:113], v[182:185], v[174:177], v[50:65]
	ds_read_b64_tr_b16 v[86:87], v220 offset:41984
	ds_read_b64_tr_b16 v[88:89], v220 offset:42496
	v_add_f32_e32 v146, v92, v146
	v_add_f32_e32 v146, v93, v146
	v_add_f32_e32 v146, v94, v146
	v_add_f32_e32 v146, v95, v146
	v_cvt_pk_bf16_f32 v158, v90, v91
	v_cvt_pk_bf16_f32 v159, v92, v93
	s_waitcnt lgkmcnt(11)
	v_mfma_f32_32x32x16_bf16 v[114:129], v[186:189], v[170:173], v[114:129]
	ds_read_b64_tr_b16 v[90:91], v220 offset:46080
	ds_read_b64_tr_b16 v[92:93], v220 offset:46592
	v_add_f32_e32 v146, v96, v146
	v_add_f32_e32 v146, v97, v146
	v_add_f32_e32 v146, v66, v146
	v_add_f32_e32 v146, v67, v146
	v_cvt_pk_bf16_f32 v160, v94, v95
	v_cvt_pk_bf16_f32 v161, v96, v97
	s_waitcnt lgkmcnt(12)
	v_mfma_f32_32x32x16_bf16 v[98:113], v[178:181], v[170:173], v[98:113]
	ds_read_b64_tr_b16 v[94:95], v220 offset:43008
	ds_read_b64_tr_b16 v[96:97], v220 offset:43520
	s_waitcnt lgkmcnt(13)
	v_mfma_f32_32x32x16_bf16 v[114:129], v[142:145], v[162:165], v[114:129]
	v_add_f32_e32 v142, v68, v146
	v_add_f32_e32 v142, v69, v142
	v_add_f32_e32 v142, v70, v142
	v_add_f32_e32 v142, v71, v142
	v_cvt_pk_bf16_f32 v150, v66, v67
	v_cvt_pk_bf16_f32 v151, v68, v69
	ds_read_b64_tr_b16 v[66:67], v220 offset:47104
	ds_read_b64_tr_b16 v[68:69], v220 offset:47616
	s_waitcnt lgkmcnt(14)
	v_mfma_f32_32x32x16_bf16 v[98:113], v[138:141], v[162:165], v[98:113]
	v_add_f32_e32 v138, v72, v142
	v_add_f32_e32 v138, v73, v138
	v_add_f32_e32 v138, v74, v138
	v_add_f32_e32 v138, v75, v138
	v_cvt_pk_bf16_f32 v152, v70, v71
	v_cvt_pk_bf16_f32 v153, v72, v73
	ds_read_b64_tr_b16 v[70:71], v220 offset:44032
	ds_read_b64_tr_b16 v[72:73], v220 offset:44544
	s_waitcnt lgkmcnt(14)
	v_mfma_f32_32x32x16_bf16 v[114:129], v[134:137], v[154:157], v[114:129]
	v_add_f32_e32 v134, v76, v138
	v_add_f32_e32 v134, v77, v134
	v_add_f32_e32 v134, v78, v134
	v_add_f32_e32 v134, v79, v134
	v_cvt_pk_bf16_f32 v146, v74, v75
	v_cvt_pk_bf16_f32 v147, v76, v77
	ds_read_b64_tr_b16 v[74:75], v220 offset:48128
	ds_read_b64_tr_b16 v[76:77], v220 offset:48640
	v_mfma_f32_32x32x16_bf16 v[98:113], v[130:133], v[154:157], v[98:113]
	v_add_f32_e32 v130, v80, v134
	v_add_f32_e32 v130, v81, v130
	v_add_f32_e32 v130, 0, v130
	v_cvt_pk_bf16_f32 v148, v78, v79
	v_cvt_pk_bf16_f32 v149, v80, v81
	s_mov_b64 s[12:13], 0x1f0000
	s_cmp_lg_u32 0, -1
	v_lshl_add_u64 v[78:79], v[210:211], 0, s[12:13]
	s_cselect_b32 s12, 0, 0
	s_add_i32 s12, s12, s5
	s_add_i32 s5, s12, 0x8000
	s_mov_b32 s13, m0
	s_mov_b32 m0, s5
	s_nop 0
	global_load_lds_dwordx4 v[78:79], off
	s_mov_b32 m0, s13
	v_add_f32_e32 v190, v199, v130
	s_waitcnt lgkmcnt(14)
	v_mfma_f32_32x32x16_bf16 v[18:33], v[166:169], v[214:217], v[18:33]
	v_exp_f32_e32 v114, v114
	v_exp_f32_e32 v115, v115
	v_exp_f32_e32 v116, v116
	v_exp_f32_e32 v117, v117
	s_waitcnt lgkmcnt(12)
	v_mfma_f32_32x32x16_bf16 v[34:49], v[166:169], v[82:85], v[34:49]
	v_exp_f32_e32 v118, v118
	v_exp_f32_e32 v119, v119
	v_exp_f32_e32 v120, v120
	v_exp_f32_e32 v121, v121
	ds_read_b128 v[78:81], v219 offset:8192
	ds_read_b128 v[178:181], v219 offset:8704
	s_waitcnt lgkmcnt(12)
	v_mfma_f32_32x32x16_bf16 v[18:33], v[158:161], v[86:89], v[18:33]
	v_exp_f32_e32 v122, v122
	v_exp_f32_e32 v123, v123
	v_exp_f32_e32 v124, v124
	v_exp_f32_e32 v125, v125
	ds_read_b128 v[86:89], v219 offset:10240
	ds_read_b128 v[182:185], v219 offset:10752
	s_waitcnt lgkmcnt(12)
	v_mfma_f32_32x32x16_bf16 v[34:49], v[158:161], v[90:93], v[34:49]
	v_exp_f32_e32 v126, v126
	v_exp_f32_e32 v127, v127
	v_exp_f32_e32 v128, v128
	v_exp_f32_e32 v129, v129
	ds_read_b128 v[90:93], v219 offset:12288
	ds_read_b128 v[186:189], v219 offset:12800
	s_waitcnt lgkmcnt(12)
	v_mfma_f32_32x32x16_bf16 v[18:33], v[150:153], v[94:97], v[18:33]
	v_exp_f32_e32 v98, v98
	v_exp_f32_e32 v99, v99
	v_exp_f32_e32 v100, v100
	v_exp_f32_e32 v101, v101
	ds_read_b128 v[94:97], v219 offset:14336
	ds_read_b128 v[82:85], v219 offset:14848
	s_waitcnt lgkmcnt(12)
	v_mfma_f32_32x32x16_bf16 v[34:49], v[150:153], v[66:69], v[34:49]
	v_exp_f32_e32 v102, v102
	v_exp_f32_e32 v103, v103
	v_exp_f32_e32 v104, v104
	v_exp_f32_e32 v105, v105
	s_waitcnt lgkmcnt(10)
	v_mfma_f32_32x32x16_bf16 v[18:33], v[146:149], v[70:73], v[18:33]
	v_exp_f32_e32 v106, v106
	v_exp_f32_e32 v107, v107
	v_exp_f32_e32 v108, v108
	v_exp_f32_e32 v109, v109
	s_waitcnt lgkmcnt(8)
	v_mfma_f32_32x32x16_bf16 v[34:49], v[146:149], v[74:77], v[34:49]
	v_exp_f32_e32 v110, v110
	v_exp_f32_e32 v111, v111
	v_exp_f32_e32 v112, v112
	v_exp_f32_e32 v113, v113
	s_waitcnt vmcnt(1) lgkmcnt(0)
	s_barrier
; #define WAIT_BAR(N) asm volatile("s_waitcnt vmcnt(" #N ") lgkmcnt(0)\n\ts_barrier":::"memory")
;   #define RESC() do{}while(0)
;   #define ROT() do{sl_prev=sl_cur;sl_cur=sl_next;sl_next=(sl_next==(NSLOT-1)*SLOTB)?0:sl_next+SLOTB;}while(0)
;   #define ENDW(tt) do{ if((tt)+3<NT){WAIT_BAR(2);} else if((tt)+2<NT){WAIT_BAR(1);} else {WAIT_BAR(0);} }while(0)
; template<int THRL> __device__ __forceinline__ void attn_unit(int b,int h,int qb,const bf16*Q,const bf16*__restrict__ K,const bf16*__restrict__ V,bf16*O,char*shm,float m2){
;     ...
;   int t=1;
;   for(;t+5<NT;t+=2){
;     STEP(pB0,pB1,pA0,pA1,t,true,true,true);     WAIT_BAR(2); RESC(); ROT();
;     STEP(pA0,pA1,pB0,pB1,t+1,true,true,true);   WAIT_BAR(2); RESC(); ROT();
;   }
;     ...
;   for(;t+1<NT;t+=2){
;     STEP(pB0,pB1,pA0,pA1,t,(t+3<NT),(t+1<NT),(t+1<NT));       ENDW(t);   RESC(); ROT();
;     STEP(pA0,pA1,pB0,pB1,t+1,(t+4<NT),(t+2<NT),(t+2<NT));     ENDW(t+1); RESC(); ROT();
	v_lshl_add_u64 v[238:239], v[212:213], 0, s[50:51]
	s_mov_b32 s98, s12
	s_mov_b32 s99, m0
	s_mov_b32 m0, s98
	s_nop 0
	global_load_lds_dwordx4 v[238:239], off
	s_mov_b32 m0, s99
	ds_read_b64_tr_b16 v[214:215], v220 offset:24576
	ds_read_b64_tr_b16 v[216:217], v220 offset:25088
	v_add_f32_e32 v66, v114, v115
	v_add_f32_e32 v66, v116, v66
	v_add_f32_e32 v66, v117, v66
	v_add_f32_e32 v66, v118, v66
	v_add_f32_e32 v66, v119, v66
	v_cvt_pk_bf16_f32 v166, v114, v115
	v_cvt_pk_bf16_f32 v167, v116, v117
	s_waitcnt lgkmcnt(9)
	v_mfma_f32_32x32x16_bf16 v[130:145], v[78:81], v[174:177], v[50:65]
	ds_read_b64_tr_b16 v[114:115], v220 offset:28672
	ds_read_b64_tr_b16 v[116:117], v220 offset:29184
	v_add_f32_e32 v66, v120, v66
	v_add_f32_e32 v66, v121, v66
	v_add_f32_e32 v66, v122, v66
	v_add_f32_e32 v146, v123, v66
	s_waitcnt lgkmcnt(10)
	v_mfma_f32_32x32x16_bf16 v[66:81], v[178:181], v[174:177], v[50:65]
	v_cvt_pk_bf16_f32 v168, v118, v119
	v_cvt_pk_bf16_f32 v169, v120, v121
	ds_read_b64_tr_b16 v[118:119], v220 offset:25600
	ds_read_b64_tr_b16 v[120:121], v220 offset:26112
	s_waitcnt lgkmcnt(11)
	v_mfma_f32_32x32x16_bf16 v[130:145], v[86:89], v[170:173], v[130:145]
	v_add_f32_e32 v86, v124, v146
	v_add_f32_e32 v86, v125, v86
	v_add_f32_e32 v86, v126, v86
	v_add_f32_e32 v146, v127, v86
	v_cvt_pk_bf16_f32 v158, v122, v123
	v_cvt_pk_bf16_f32 v159, v124, v125
	ds_read_b64_tr_b16 v[86:87], v220 offset:29696
	ds_read_b64_tr_b16 v[88:89], v220 offset:30208
	s_waitcnt lgkmcnt(12)
	v_mfma_f32_32x32x16_bf16 v[66:81], v[182:185], v[170:173], v[66:81]
	v_add_f32_e32 v122, v128, v146
	v_add_f32_e32 v122, v129, v122
	v_add_f32_e32 v122, v98, v122
	v_add_f32_e32 v146, v99, v122
	v_cvt_pk_bf16_f32 v160, v126, v127
	v_cvt_pk_bf16_f32 v161, v128, v129
	ds_read_b64_tr_b16 v[122:123], v220 offset:26624
	ds_read_b64_tr_b16 v[124:125], v220 offset:27136
	s_waitcnt lgkmcnt(13)
	v_mfma_f32_32x32x16_bf16 v[130:145], v[90:93], v[162:165], v[130:145]
	v_add_f32_e32 v90, v100, v146
	v_add_f32_e32 v90, v101, v90
	v_add_f32_e32 v90, v102, v90
	v_add_f32_e32 v126, v103, v90
	v_cvt_pk_bf16_f32 v150, v98, v99
	v_cvt_pk_bf16_f32 v151, v100, v101
	ds_read_b64_tr_b16 v[90:91], v220 offset:30720
	ds_read_b64_tr_b16 v[92:93], v220 offset:31232
	s_waitcnt lgkmcnt(14)
	v_mfma_f32_32x32x16_bf16 v[66:81], v[186:189], v[162:165], v[66:81]
	v_add_f32_e32 v98, v104, v126
	v_add_f32_e32 v98, v105, v98
	v_add_f32_e32 v98, v106, v98
	v_add_f32_e32 v98, v107, v98
	v_cvt_pk_bf16_f32 v152, v102, v103
	v_cvt_pk_bf16_f32 v153, v104, v105
	ds_read_b64_tr_b16 v[102:103], v220 offset:27648
	ds_read_b64_tr_b16 v[104:105], v220 offset:28160
	s_waitcnt lgkmcnt(14)
	v_mfma_f32_32x32x16_bf16 v[130:145], v[94:97], v[154:157], v[130:145]
	v_add_f32_e32 v94, v108, v98
	v_add_f32_e32 v94, v109, v94
	v_add_f32_e32 v94, v110, v94
	v_add_f32_e32 v98, v111, v94
	v_cvt_pk_bf16_f32 v146, v106, v107
	v_cvt_pk_bf16_f32 v147, v108, v109
	ds_read_b64_tr_b16 v[94:95], v220 offset:31744
	ds_read_b64_tr_b16 v[96:97], v220 offset:32256
	v_mfma_f32_32x32x16_bf16 v[66:81], v[82:85], v[154:157], v[66:81]
	v_add_f32_e32 v82, v112, v98
	v_add_f32_e32 v82, v113, v82
	v_add_f32_e32 v82, 0, v82
	v_cvt_pk_bf16_f32 v148, v110, v111
	v_cvt_pk_bf16_f32 v149, v112, v113
	s_nop 0
	v_add_f32_e32 v190, v190, v82
	v_lshl_add_u64 v[238:239], v[212:213], 0, s[52:53]
	s_mov_b64 s[14:15], 0x1f4000
	v_lshl_add_u64 v[82:83], v[210:211], 0, s[14:15]
	s_add_i32 s12, s12, 0xa000
	s_mov_b32 s13, m0
	s_mov_b32 m0, s12
	s_nop 0
	global_load_lds_dwordx4 v[82:83], off
	s_mov_b32 m0, s13
	s_waitcnt lgkmcnt(14)
	v_mfma_f32_32x32x16_bf16 v[18:33], v[166:169], v[214:217], v[18:33]
	v_exp_f32_e32 v130, v130
	v_exp_f32_e32 v131, v131
	v_exp_f32_e32 v132, v132
	v_exp_f32_e32 v133, v133
	s_waitcnt lgkmcnt(12)
	v_mfma_f32_32x32x16_bf16 v[34:49], v[166:169], v[114:117], v[34:49]
	v_exp_f32_e32 v134, v134
	v_exp_f32_e32 v135, v135
	v_exp_f32_e32 v136, v136
	v_exp_f32_e32 v137, v137
	ds_read_b128 v[82:85], v219 offset:16384
	ds_read_b128 v[106:109], v219 offset:16896
	s_waitcnt lgkmcnt(12)
	v_mfma_f32_32x32x16_bf16 v[18:33], v[158:161], v[118:121], v[18:33]
	v_exp_f32_e32 v138, v138
	v_exp_f32_e32 v139, v139
	v_exp_f32_e32 v140, v140
	v_exp_f32_e32 v141, v141
	ds_read_b128 v[110:113], v219 offset:18432
	ds_read_b128 v[178:181], v219 offset:18944
	s_waitcnt lgkmcnt(12)
	v_mfma_f32_32x32x16_bf16 v[34:49], v[158:161], v[86:89], v[34:49]
	v_exp_f32_e32 v142, v142
	v_exp_f32_e32 v143, v143
	v_exp_f32_e32 v144, v144
	v_exp_f32_e32 v145, v145
	ds_read_b128 v[182:185], v219 offset:20480
	ds_read_b128 v[186:189], v219 offset:20992
	s_waitcnt lgkmcnt(12)
	v_mfma_f32_32x32x16_bf16 v[18:33], v[150:153], v[122:125], v[18:33]
	v_exp_f32_e32 v66, v66
	v_exp_f32_e32 v67, v67
	v_exp_f32_e32 v68, v68
	v_exp_f32_e32 v69, v69
	ds_read_b128 v[212:215], v219 offset:22528
	ds_read_b128 v[98:101], v219 offset:23040
	s_waitcnt lgkmcnt(12)
	v_mfma_f32_32x32x16_bf16 v[34:49], v[150:153], v[90:93], v[34:49]
	v_exp_f32_e32 v70, v70
	v_exp_f32_e32 v71, v71
	v_exp_f32_e32 v72, v72
	v_exp_f32_e32 v73, v73
	s_waitcnt lgkmcnt(10)
	v_mfma_f32_32x32x16_bf16 v[18:33], v[146:149], v[102:105], v[18:33]
	v_exp_f32_e32 v74, v74
	v_exp_f32_e32 v75, v75
	v_exp_f32_e32 v76, v76
	v_exp_f32_e32 v77, v77
	s_waitcnt lgkmcnt(8)
	v_mfma_f32_32x32x16_bf16 v[34:49], v[146:149], v[94:97], v[34:49]
	v_exp_f32_e32 v78, v78
	v_exp_f32_e32 v79, v79
	v_exp_f32_e32 v80, v80
	v_exp_f32_e32 v81, v81
	s_waitcnt vmcnt(1) lgkmcnt(0)
	s_barrier
; #define WAIT_BAR(N) asm volatile("s_waitcnt vmcnt(" #N ") lgkmcnt(0)\n\ts_barrier":::"memory")
;   #define RESC() do{}while(0)
;   #define ROT() do{sl_prev=sl_cur;sl_cur=sl_next;sl_next=(sl_next==(NSLOT-1)*SLOTB)?0:sl_next+SLOTB;}while(0)
;   #define ENDW(tt) do{ if((tt)+3<NT){WAIT_BAR(2);} else if((tt)+2<NT){WAIT_BAR(1);} else {WAIT_BAR(0);} }while(0)
; template<int THRL> __device__ __forceinline__ void attn_unit(int b,int h,int qb,const bf16*Q,const bf16*__restrict__ K,const bf16*__restrict__ V,bf16*O,char*shm,float m2){
;     ...
;   int t=1;
;   for(;t+5<NT;t+=2){
;     STEP(pB0,pB1,pA0,pA1,t,true,true,true);     WAIT_BAR(2); RESC(); ROT();
;     STEP(pA0,pA1,pB0,pB1,t+1,true,true,true);   WAIT_BAR(2); RESC(); ROT();
;   }
;     ...
;   for(;t+1<NT;t+=2){
;     STEP(pB0,pB1,pA0,pA1,t,(t+3<NT),(t+1<NT),(t+1<NT));       ENDW(t);   RESC(); ROT();
;     STEP(pA0,pA1,pB0,pB1,t+1,(t+4<NT),(t+2<NT),(t+2<NT));     ENDW(t+1); RESC(); ROT();
;   }
	s_add_i32 s98, s5, 0xffffa000
	s_mov_b32 s99, m0
	s_mov_b32 m0, s98
	s_nop 0
	global_load_lds_dwordx4 v[238:239], off
	s_mov_b32 m0, s99
	ds_read_b64_tr_b16 v[102:103], v220 offset:32768
	ds_read_b64_tr_b16 v[104:105], v220 offset:33280
	v_add_f32_e32 v86, v130, v131
	v_add_f32_e32 v86, v132, v86
	v_add_f32_e32 v86, v133, v86
	v_add_f32_e32 v86, v134, v86
	v_add_f32_e32 v86, v135, v86
	v_cvt_pk_bf16_f32 v166, v130, v131
	v_cvt_pk_bf16_f32 v167, v132, v133
	s_waitcnt lgkmcnt(9)
	v_mfma_f32_32x32x16_bf16 v[114:129], v[82:85], v[174:177], v[50:65]
	ds_read_b64_tr_b16 v[130:131], v220 offset:36864
	ds_read_b64_tr_b16 v[132:133], v220 offset:37376
	v_add_f32_e32 v82, v136, v86
	v_add_f32_e32 v82, v137, v82
	v_add_f32_e32 v82, v138, v82
	v_add_f32_e32 v146, v139, v82
	v_cvt_pk_bf16_f32 v168, v134, v135
	v_cvt_pk_bf16_f32 v169, v136, v137
	s_waitcnt lgkmcnt(10)
	v_mfma_f32_32x32x16_bf16 v[82:97], v[106:109], v[174:177], v[50:65]
	ds_read_b64_tr_b16 v[106:107], v220 offset:33792
	ds_read_b64_tr_b16 v[108:109], v220 offset:34304
	s_waitcnt lgkmcnt(11)
	v_mfma_f32_32x32x16_bf16 v[114:129], v[110:113], v[170:173], v[114:129]
	v_add_f32_e32 v110, v140, v146
	v_add_f32_e32 v110, v141, v110
	v_add_f32_e32 v110, v142, v110
	v_add_f32_e32 v134, v143, v110
	v_cvt_pk_bf16_f32 v158, v138, v139
	v_cvt_pk_bf16_f32 v159, v140, v141
	ds_read_b64_tr_b16 v[110:111], v220 offset:37888
	ds_read_b64_tr_b16 v[112:113], v220 offset:38400
	v_add_f32_e32 v134, v144, v134
	v_add_f32_e32 v134, v145, v134
	v_add_f32_e32 v134, v66, v134
	v_add_f32_e32 v138, v67, v134
	v_cvt_pk_bf16_f32 v160, v142, v143
	v_cvt_pk_bf16_f32 v161, v144, v145
	s_waitcnt lgkmcnt(12)
	v_mfma_f32_32x32x16_bf16 v[82:97], v[178:181], v[170:173], v[82:97]
	ds_read_b64_tr_b16 v[134:135], v220 offset:34816
	ds_read_b64_tr_b16 v[136:137], v220 offset:35328
	v_add_f32_e32 v138, v68, v138
	v_add_f32_e32 v138, v69, v138
	v_add_f32_e32 v138, v70, v138
	v_add_f32_e32 v138, v71, v138
	v_cvt_pk_bf16_f32 v150, v66, v67
	v_cvt_pk_bf16_f32 v151, v68, v69
	s_waitcnt lgkmcnt(13)
	v_mfma_f32_32x32x16_bf16 v[114:129], v[182:185], v[162:165], v[114:129]
	ds_read_b64_tr_b16 v[66:67], v220 offset:38912
	ds_read_b64_tr_b16 v[68:69], v220 offset:39424
	v_add_f32_e32 v138, v72, v138
	v_add_f32_e32 v138, v73, v138
	v_add_f32_e32 v138, v74, v138
	v_add_f32_e32 v138, v75, v138
	v_cvt_pk_bf16_f32 v152, v70, v71
	v_cvt_pk_bf16_f32 v153, v72, v73
	s_waitcnt lgkmcnt(14)
	v_mfma_f32_32x32x16_bf16 v[82:97], v[186:189], v[162:165], v[82:97]
	ds_read_b64_tr_b16 v[70:71], v220 offset:35840
	ds_read_b64_tr_b16 v[72:73], v220 offset:36352
	v_add_f32_e32 v138, v76, v138
	v_add_f32_e32 v138, v77, v138
	v_add_f32_e32 v138, v78, v138
	v_add_f32_e32 v138, v79, v138
	v_cvt_pk_bf16_f32 v146, v74, v75
	v_cvt_pk_bf16_f32 v147, v76, v77
	s_waitcnt lgkmcnt(14)
	v_mfma_f32_32x32x16_bf16 v[114:129], v[212:215], v[154:157], v[114:129]
	ds_read_b64_tr_b16 v[74:75], v220 offset:39936
	ds_read_b64_tr_b16 v[76:77], v220 offset:40448
	v_mfma_f32_32x32x16_bf16 v[82:97], v[98:101], v[154:157], v[82:97]
	v_add_f32_e32 v98, v80, v138
	v_add_f32_e32 v98, v81, v98
	v_add_f32_e32 v98, 0, v98
	v_cvt_pk_bf16_f32 v148, v78, v79
	v_cvt_pk_bf16_f32 v149, v80, v81
	v_lshl_add_u64 v[78:79], v[210:211], 0, s[50:51]
	s_mov_b32 s12, m0
	s_mov_b32 m0, s4
	s_nop 0
	global_load_lds_dwordx4 v[78:79], off
	s_mov_b32 m0, s12
	v_add_f32_e32 v190, v190, v98
	s_waitcnt lgkmcnt(14)
	v_mfma_f32_32x32x16_bf16 v[18:33], v[166:169], v[102:105], v[18:33]
	v_exp_f32_e32 v114, v114
	v_exp_f32_e32 v115, v115
	v_exp_f32_e32 v116, v116
	v_exp_f32_e32 v117, v117
	s_waitcnt lgkmcnt(12)
	v_mfma_f32_32x32x16_bf16 v[34:49], v[166:169], v[130:133], v[34:49]
	v_exp_f32_e32 v118, v118
	v_exp_f32_e32 v119, v119
	v_exp_f32_e32 v120, v120
	v_exp_f32_e32 v121, v121
	ds_read_b128 v[78:81], v219
	ds_read_b128 v[138:141], v219 offset:512
	s_waitcnt lgkmcnt(12)
	v_mfma_f32_32x32x16_bf16 v[18:33], v[158:161], v[106:109], v[18:33]
	v_exp_f32_e32 v122, v122
	v_exp_f32_e32 v123, v123
	v_exp_f32_e32 v124, v124
	v_exp_f32_e32 v125, v125
	ds_read_b128 v[142:145], v219 offset:2048
	ds_read_b128 v[178:181], v219 offset:2560
	s_waitcnt lgkmcnt(12)
	v_mfma_f32_32x32x16_bf16 v[34:49], v[158:161], v[110:113], v[34:49]
	v_exp_f32_e32 v126, v126
	v_exp_f32_e32 v127, v127
	v_exp_f32_e32 v128, v128
	v_exp_f32_e32 v129, v129
	ds_read_b128 v[182:185], v219 offset:4096
	ds_read_b128 v[186:189], v219 offset:4608
	s_waitcnt lgkmcnt(12)
	v_mfma_f32_32x32x16_bf16 v[18:33], v[150:153], v[134:137], v[18:33]
	v_exp_f32_e32 v82, v82
	v_exp_f32_e32 v83, v83
	v_exp_f32_e32 v84, v84
	v_exp_f32_e32 v85, v85
	ds_read_b128 v[134:137], v219 offset:6144
	ds_read_b128 v[130:133], v219 offset:6656
	s_waitcnt lgkmcnt(12)
	v_mfma_f32_32x32x16_bf16 v[34:49], v[150:153], v[66:69], v[34:49]
	v_exp_f32_e32 v86, v86
	v_exp_f32_e32 v87, v87
	v_exp_f32_e32 v88, v88
	v_exp_f32_e32 v89, v89
	s_waitcnt lgkmcnt(10)
	v_mfma_f32_32x32x16_bf16 v[18:33], v[146:149], v[70:73], v[18:33]
	v_exp_f32_e32 v90, v90
	v_exp_f32_e32 v91, v91
	v_exp_f32_e32 v92, v92
	v_exp_f32_e32 v93, v93
	s_waitcnt lgkmcnt(8)
	v_mfma_f32_32x32x16_bf16 v[34:49], v[146:149], v[74:77], v[34:49]
	v_exp_f32_e32 v94, v94
	v_exp_f32_e32 v95, v95
	v_exp_f32_e32 v96, v96
	v_exp_f32_e32 v97, v97
	s_waitcnt vmcnt(1) lgkmcnt(0)
	s_barrier
; #define WAIT_BAR(N) asm volatile("s_waitcnt vmcnt(" #N ") lgkmcnt(0)\n\ts_barrier":::"memory")
;   #define RESC() do{}while(0)
;   #define ROT() do{sl_prev=sl_cur;sl_cur=sl_next;sl_next=(sl_next==(NSLOT-1)*SLOTB)?0:sl_next+SLOTB;}while(0)
;   #define ENDW(tt) do{ if((tt)+3<NT){WAIT_BAR(2);} else if((tt)+2<NT){WAIT_BAR(1);} else {WAIT_BAR(0);} }while(0)
; template<int THRL> __device__ __forceinline__ void attn_unit(int b,int h,int qb,const bf16*Q,const bf16*__restrict__ K,const bf16*__restrict__ V,bf16*O,char*shm,float m2){
;     ...
;   int t=1;
;   for(;t+5<NT;t+=2){
;     STEP(pB0,pB1,pA0,pA1,t,true,true,true);     WAIT_BAR(2); RESC(); ROT();
;     STEP(pA0,pA1,pB0,pB1,t+1,true,true,true);   WAIT_BAR(2); RESC(); ROT();
;   }
;     ...
;   for(;t+1<NT;t+=2){
;     STEP(pB0,pB1,pA0,pA1,t,(t+3<NT),(t+1<NT),(t+1<NT));       ENDW(t);   RESC(); ROT();
;     STEP(pA0,pA1,pB0,pB1,t+1,(t+4<NT),(t+2<NT),(t+2<NT));     ENDW(t+1); RESC(); ROT();
;   }
	ds_read_b64_tr_b16 v[212:213], v220 offset:40960
	ds_read_b64_tr_b16 v[214:215], v220 offset:41472
	v_add_f32_e32 v66, v114, v115
	v_add_f32_e32 v66, v116, v66
	v_add_f32_e32 v66, v117, v66
	v_add_f32_e32 v66, v118, v66
	v_add_f32_e32 v66, v119, v66
	v_cvt_pk_bf16_f32 v166, v114, v115
	v_cvt_pk_bf16_f32 v167, v116, v117
	s_waitcnt lgkmcnt(9)
	v_mfma_f32_32x32x16_bf16 v[98:113], v[78:81], v[174:177], v[50:65]
	ds_read_b64_tr_b16 v[114:115], v220 offset:45056
	ds_read_b64_tr_b16 v[116:117], v220 offset:45568
	v_add_f32_e32 v66, v120, v66
	v_add_f32_e32 v66, v121, v66
	v_add_f32_e32 v66, v122, v66
	v_add_f32_e32 v146, v123, v66
	s_waitcnt lgkmcnt(10)
	v_mfma_f32_32x32x16_bf16 v[66:81], v[138:141], v[174:177], v[50:65]
	v_cvt_pk_bf16_f32 v168, v118, v119
	v_cvt_pk_bf16_f32 v169, v120, v121
	ds_read_b64_tr_b16 v[138:139], v220 offset:41984
	ds_read_b64_tr_b16 v[140:141], v220 offset:42496
	v_add_f32_e32 v118, v124, v146
	v_add_f32_e32 v118, v125, v118
	v_add_f32_e32 v118, v126, v118
	v_add_f32_e32 v118, v127, v118
	v_cvt_pk_bf16_f32 v158, v122, v123
	v_cvt_pk_bf16_f32 v159, v124, v125
	s_waitcnt lgkmcnt(11)
	v_mfma_f32_32x32x16_bf16 v[98:113], v[142:145], v[170:173], v[98:113]
	ds_read_b64_tr_b16 v[120:121], v220 offset:46080
	ds_read_b64_tr_b16 v[122:123], v220 offset:46592
	s_waitcnt lgkmcnt(12)
	v_mfma_f32_32x32x16_bf16 v[66:81], v[178:181], v[170:173], v[66:81]
	v_add_f32_e32 v118, v128, v118
	v_add_f32_e32 v118, v129, v118
	v_add_f32_e32 v118, v82, v118
	v_add_f32_e32 v118, v83, v118
	v_cvt_pk_bf16_f32 v160, v126, v127
	v_cvt_pk_bf16_f32 v161, v128, v129
	ds_read_b64_tr_b16 v[124:125], v220 offset:43008
	ds_read_b64_tr_b16 v[126:127], v220 offset:43520
	v_add_f32_e32 v118, v84, v118
	v_add_f32_e32 v118, v85, v118
	v_add_f32_e32 v118, v86, v118
	v_add_f32_e32 v118, v87, v118
	v_cvt_pk_bf16_f32 v150, v82, v83
	v_cvt_pk_bf16_f32 v151, v84, v85
	s_waitcnt lgkmcnt(13)
	v_mfma_f32_32x32x16_bf16 v[98:113], v[182:185], v[162:165], v[98:113]
	ds_read_b64_tr_b16 v[82:83], v220 offset:47104
	ds_read_b64_tr_b16 v[84:85], v220 offset:47616
	s_waitcnt lgkmcnt(14)
	v_mfma_f32_32x32x16_bf16 v[66:81], v[186:189], v[162:165], v[66:81]
	v_add_f32_e32 v118, v88, v118
	v_add_f32_e32 v118, v89, v118
	v_add_f32_e32 v118, v90, v118
	v_add_f32_e32 v118, v91, v118
	v_cvt_pk_bf16_f32 v152, v86, v87
	v_cvt_pk_bf16_f32 v153, v88, v89
	ds_read_b64_tr_b16 v[86:87], v220 offset:44032
	ds_read_b64_tr_b16 v[88:89], v220 offset:44544
	v_add_f32_e32 v118, v92, v118
	v_add_f32_e32 v118, v93, v118
	v_add_f32_e32 v118, v94, v118
	v_add_f32_e32 v118, v95, v118
	v_cvt_pk_bf16_f32 v146, v90, v91
	v_cvt_pk_bf16_f32 v147, v92, v93
	s_waitcnt lgkmcnt(14)
	v_mfma_f32_32x32x16_bf16 v[98:113], v[134:137], v[154:157], v[98:113]
	ds_read_b64_tr_b16 v[90:91], v220 offset:48128
	ds_read_b64_tr_b16 v[92:93], v220 offset:48640
	v_mfma_f32_32x32x16_bf16 v[66:81], v[130:133], v[154:157], v[66:81]
	v_add_f32_e32 v118, v96, v118
	v_add_f32_e32 v118, v97, v118
	v_add_f32_e32 v118, 0, v118
	v_cvt_pk_bf16_f32 v148, v94, v95
	v_cvt_pk_bf16_f32 v149, v96, v97
	v_lshl_add_u64 v[94:95], v[210:211], 0, s[52:53]
	s_mov_b32 s4, m0
	s_mov_b32 m0, s5
	s_nop 0
	global_load_lds_dwordx4 v[94:95], off
	s_mov_b32 m0, s4
	v_add_f32_e32 v118, v190, v118
	s_waitcnt lgkmcnt(14)
	v_mfma_f32_32x32x16_bf16 v[18:33], v[166:169], v[212:215], v[18:33]
	v_exp_f32_e32 v98, v98
	v_exp_f32_e32 v99, v99
	v_exp_f32_e32 v100, v100
	v_exp_f32_e32 v101, v101
	s_waitcnt lgkmcnt(12)
	v_mfma_f32_32x32x16_bf16 v[34:49], v[166:169], v[114:117], v[34:49]
	v_exp_f32_e32 v102, v102
	v_exp_f32_e32 v103, v103
	v_exp_f32_e32 v104, v104
	v_exp_f32_e32 v105, v105
	ds_read_b128 v[128:131], v219 offset:8192
	ds_read_b128 v[132:135], v219 offset:8704
	s_waitcnt lgkmcnt(12)
	v_mfma_f32_32x32x16_bf16 v[18:33], v[158:161], v[138:141], v[18:33]
	v_exp_f32_e32 v106, v106
	v_exp_f32_e32 v107, v107
	v_exp_f32_e32 v108, v108
	v_exp_f32_e32 v109, v109
	ds_read_b128 v[136:139], v219 offset:10240
	ds_read_b128 v[140:143], v219 offset:10752
	s_waitcnt lgkmcnt(12)
	v_mfma_f32_32x32x16_bf16 v[34:49], v[158:161], v[120:123], v[34:49]
	v_exp_f32_e32 v110, v110
	v_exp_f32_e32 v111, v111
	v_exp_f32_e32 v112, v112
	v_exp_f32_e32 v113, v113
	ds_read_b128 v[120:123], v219 offset:12288
	ds_read_b128 v[178:181], v219 offset:12800
	s_waitcnt lgkmcnt(12)
	v_mfma_f32_32x32x16_bf16 v[18:33], v[150:153], v[124:127], v[18:33]
	v_exp_f32_e32 v66, v66
	v_exp_f32_e32 v67, v67
	v_exp_f32_e32 v68, v68
	v_exp_f32_e32 v69, v69
	ds_read_b128 v[124:127], v219 offset:14336
	ds_read_b128 v[114:117], v219 offset:14848
	s_waitcnt lgkmcnt(12)
	v_mfma_f32_32x32x16_bf16 v[34:49], v[150:153], v[82:85], v[34:49]
	v_exp_f32_e32 v70, v70
	v_exp_f32_e32 v71, v71
	v_exp_f32_e32 v72, v72
	v_exp_f32_e32 v73, v73
	s_waitcnt lgkmcnt(10)
	v_mfma_f32_32x32x16_bf16 v[18:33], v[146:149], v[86:89], v[18:33]
	v_exp_f32_e32 v74, v74
	v_exp_f32_e32 v75, v75
	v_exp_f32_e32 v76, v76
	v_exp_f32_e32 v77, v77
	s_waitcnt lgkmcnt(8)
	v_mfma_f32_32x32x16_bf16 v[34:49], v[146:149], v[90:93], v[34:49]
	v_exp_f32_e32 v78, v78
	v_exp_f32_e32 v79, v79
	v_exp_f32_e32 v80, v80
	v_exp_f32_e32 v81, v81
	s_waitcnt vmcnt(0) lgkmcnt(0)
	s_barrier
; #define WAIT_BAR(N) asm volatile("s_waitcnt vmcnt(" #N ") lgkmcnt(0)\n\ts_barrier":::"memory")
;   #define RESC() do{}while(0)
;   #define ROT() do{sl_prev=sl_cur;sl_cur=sl_next;sl_next=(sl_next==(NSLOT-1)*SLOTB)?0:sl_next+SLOTB;}while(0)
;   #define ENDW(tt) do{ if((tt)+3<NT){WAIT_BAR(2);} else if((tt)+2<NT){WAIT_BAR(1);} else {WAIT_BAR(0);} }while(0)
; template<int THRL> __device__ __forceinline__ void attn_unit(int b,int h,int qb,const bf16*Q,const bf16*__restrict__ K,const bf16*__restrict__ V,bf16*O,char*shm,float m2){
;     ...
;   int t=1;
;   for(;t+5<NT;t+=2){
;     STEP(pB0,pB1,pA0,pA1,t,true,true,true);     WAIT_BAR(2); RESC(); ROT();
;     STEP(pA0,pA1,pB0,pB1,t+1,true,true,true);   WAIT_BAR(2); RESC(); ROT();
;   }
;     ...
;   for(;t+1<NT;t+=2){
;     STEP(pB0,pB1,pA0,pA1,t,(t+3<NT),(t+1<NT),(t+1<NT));       ENDW(t);   RESC(); ROT();
;     STEP(pA0,pA1,pB0,pB1,t+1,(t+4<NT),(t+2<NT),(t+2<NT));     ENDW(t+1); RESC(); ROT();
;   }
;   STEP(pB0,pB1,pA0,pA1,NT-1,false,false,false); RESC();
	ds_read_b64_tr_b16 v[182:183], v220 offset:24576
	ds_read_b64_tr_b16 v[184:185], v220 offset:25088
	v_add_f32_e32 v82, v98, v99
	v_add_f32_e32 v82, v100, v82
	v_add_f32_e32 v82, v101, v82
	v_add_f32_e32 v82, v102, v82
	v_add_f32_e32 v119, v103, v82
	v_cvt_pk_bf16_f32 v166, v98, v99
	v_cvt_pk_bf16_f32 v167, v100, v101
	s_waitcnt lgkmcnt(9)
	v_mfma_f32_32x32x16_bf16 v[82:97], v[128:131], v[174:177], v[50:65]
	ds_read_b64_tr_b16 v[98:99], v220 offset:28672
	ds_read_b64_tr_b16 v[100:101], v220 offset:29184
	s_waitcnt lgkmcnt(10)
	v_mfma_f32_32x32x16_bf16 v[50:65], v[132:135], v[174:177], v[50:65]
	v_add_f32_e32 v119, v104, v119
	v_add_f32_e32 v119, v105, v119
	v_add_f32_e32 v119, v106, v119
	v_add_f32_e32 v119, v107, v119
	v_cvt_pk_bf16_f32 v168, v102, v103
	v_cvt_pk_bf16_f32 v169, v104, v105
	ds_read_b64_tr_b16 v[102:103], v220 offset:25600
	ds_read_b64_tr_b16 v[104:105], v220 offset:26112
	v_add_f32_e32 v119, v108, v119
	v_add_f32_e32 v119, v109, v119
	v_add_f32_e32 v119, v110, v119
	v_add_f32_e32 v119, v111, v119
	v_cvt_pk_bf16_f32 v158, v106, v107
	v_cvt_pk_bf16_f32 v159, v108, v109
	s_waitcnt lgkmcnt(11)
	v_mfma_f32_32x32x16_bf16 v[82:97], v[136:139], v[170:173], v[82:97]
	ds_read_b64_tr_b16 v[106:107], v220 offset:29696
	ds_read_b64_tr_b16 v[108:109], v220 offset:30208
	s_waitcnt lgkmcnt(12)
	v_mfma_f32_32x32x16_bf16 v[50:65], v[140:143], v[170:173], v[50:65]
	v_add_f32_e32 v119, v112, v119
	v_add_f32_e32 v119, v113, v119
	v_add_f32_e32 v119, v66, v119
	v_add_f32_e32 v119, v67, v119
	v_cvt_pk_bf16_f32 v160, v110, v111
	v_cvt_pk_bf16_f32 v161, v112, v113
	ds_read_b64_tr_b16 v[110:111], v220 offset:26624
	ds_read_b64_tr_b16 v[112:113], v220 offset:27136
	v_add_f32_e32 v119, v68, v119
	v_add_f32_e32 v119, v69, v119
	v_add_f32_e32 v119, v70, v119
	v_add_f32_e32 v119, v71, v119
	v_cvt_pk_bf16_f32 v150, v66, v67
	v_cvt_pk_bf16_f32 v151, v68, v69
	s_waitcnt lgkmcnt(13)
	v_mfma_f32_32x32x16_bf16 v[82:97], v[120:123], v[162:165], v[82:97]
	ds_read_b64_tr_b16 v[66:67], v220 offset:30720
	ds_read_b64_tr_b16 v[68:69], v220 offset:31232
	s_waitcnt lgkmcnt(14)
	v_mfma_f32_32x32x16_bf16 v[50:65], v[178:181], v[162:165], v[50:65]
	v_add_f32_e32 v119, v72, v119
	v_add_f32_e32 v119, v73, v119
	v_add_f32_e32 v119, v74, v119
	v_add_f32_e32 v119, v75, v119
	v_cvt_pk_bf16_f32 v152, v70, v71
	v_cvt_pk_bf16_f32 v153, v72, v73
	ds_read_b64_tr_b16 v[70:71], v220 offset:27648
	ds_read_b64_tr_b16 v[72:73], v220 offset:28160
	v_add_f32_e32 v119, v76, v119
	v_add_f32_e32 v119, v77, v119
	v_add_f32_e32 v119, v78, v119
	v_add_f32_e32 v119, v79, v119
	v_cvt_pk_bf16_f32 v146, v74, v75
	v_cvt_pk_bf16_f32 v147, v76, v77
	s_waitcnt lgkmcnt(14)
	v_mfma_f32_32x32x16_bf16 v[82:97], v[124:127], v[154:157], v[82:97]
	ds_read_b64_tr_b16 v[74:75], v220 offset:31744
	ds_read_b64_tr_b16 v[76:77], v220 offset:32256
	v_mfma_f32_32x32x16_bf16 v[50:65], v[114:117], v[154:157], v[50:65]
	v_add_f32_e32 v114, v80, v119
	v_add_f32_e32 v114, v81, v114
	v_add_f32_e32 v114, 0, v114
	v_cvt_pk_bf16_f32 v148, v78, v79
	v_cvt_pk_bf16_f32 v149, v80, v81
	s_waitcnt lgkmcnt(14)
	v_mfma_f32_32x32x16_bf16 v[18:33], v[166:169], v[182:185], v[18:33]
	s_nop 1
	v_exp_f32_e32 v82, v82
	v_exp_f32_e32 v83, v83
	v_exp_f32_e32 v84, v84
	v_exp_f32_e32 v85, v85
	s_waitcnt lgkmcnt(12)
	v_mfma_f32_32x32x16_bf16 v[34:49], v[166:169], v[98:101], v[34:49]
	v_exp_f32_e32 v86, v86
	v_exp_f32_e32 v87, v87
	v_exp_f32_e32 v88, v88
	v_exp_f32_e32 v89, v89
	s_waitcnt lgkmcnt(10)
	v_mfma_f32_32x32x16_bf16 v[18:33], v[158:161], v[102:105], v[18:33]
	v_exp_f32_e32 v90, v90
	v_exp_f32_e32 v91, v91
	v_exp_f32_e32 v92, v92
	v_exp_f32_e32 v93, v93
	s_waitcnt lgkmcnt(8)
	v_mfma_f32_32x32x16_bf16 v[34:49], v[158:161], v[106:109], v[34:49]
	v_exp_f32_e32 v94, v94
	v_exp_f32_e32 v95, v95
	v_exp_f32_e32 v96, v96
	v_exp_f32_e32 v97, v97
	s_waitcnt lgkmcnt(6)
; #define SBAR() __builtin_amdgcn_sched_barrier(0)
; #define WAIT_BAR(N) asm volatile("s_waitcnt vmcnt(" #N ") lgkmcnt(0)\n\ts_barrier":::"memory")
;   #define RESC() do{}while(0)
;   #define ROT() do{sl_prev=sl_cur;sl_cur=sl_next;sl_next=(sl_next==(NSLOT-1)*SLOTB)?0:sl_next+SLOTB;}while(0)
;   #define PKW(P,B) cvtpk_s(P[B],P[B+1])
;   #define ENDW(tt) do{ if((tt)+3<NT){WAIT_BAR(2);} else if((tt)+2<NT){WAIT_BAR(1);} else {WAIT_BAR(0);} }while(0)
; template<int THRL> __device__ __forceinline__ void attn_unit(int b,int h,int qb,const bf16*Q,const bf16*__restrict__ K,const bf16*__restrict__ V,bf16*O,char*shm,float m2){
;     ...
;   int t=1;
;   for(;t+5<NT;t+=2){
;     STEP(pB0,pB1,pA0,pA1,t,true,true,true);     WAIT_BAR(2); RESC(); ROT();
;     STEP(pA0,pA1,pB0,pB1,t+1,true,true,true);   WAIT_BAR(2); RESC(); ROT();
;   }
;     ...
;   for(;t+1<NT;t+=2){
;     STEP(pB0,pB1,pA0,pA1,t,(t+3<NT),(t+1<NT),(t+1<NT));       ENDW(t);   RESC(); ROT();
;     STEP(pA0,pA1,pB0,pB1,t+1,(t+4<NT),(t+2<NT),(t+2<NT));     ENDW(t+1); RESC(); ROT();
;   }
;   STEP(pB0,pB1,pA0,pA1,NT-1,false,false,false); RESC();
;   { float sacc=pB0[0]+pB0[1]; _Pragma("unroll") for(int r=2;r<16;++r)sacc+=pB0[r]; _Pragma("unroll") for(int r=0;r<16;++r)sacc+=pB1[r]; l_reg+=sacc;
;     pw0=(u32x4){PKW(pB0,0),PKW(pB0,2),PKW(pB0,4),PKW(pB0,6)};pw1=(u32x4){PKW(pB0,8),PKW(pB0,10),PKW(pB0,12),PKW(pB0,14)};pw2=(u32x4){PKW(pB1,0),PKW(pB1,2),PKW(pB1,4),PKW(pB1,6)};pw3=(u32x4){PKW(pB1,8),PKW(pB1,10),PKW(pB1,12),PKW(pB1,14)};
;     SBAR(); pv(o,vb0+sl_cur,PAF(0),PAF(1),PAF(2),PAF(3)); }
;     ...
;   {auto rr=__builtin_amdgcn_permlane32_swap(__float_as_uint(l_reg),__float_as_uint(l_reg),false,false);l_reg=__uint_as_float(rr[0])+__uint_as_float(rr[1]);}
;   if(hi==0)wsf[32+r32]=l_reg;asm volatile("s_waitcnt lgkmcnt(0)":::"memory");
	v_mfma_f32_32x32x16_bf16 v[18:33], v[150:153], v[110:113], v[18:33]
	v_exp_f32_e32 v50, v50
	v_exp_f32_e32 v51, v51
	v_exp_f32_e32 v52, v52
	v_exp_f32_e32 v53, v53
	s_waitcnt lgkmcnt(4)
	v_mfma_f32_32x32x16_bf16 v[34:49], v[150:153], v[66:69], v[34:49]
	v_exp_f32_e32 v54, v54
	v_exp_f32_e32 v55, v55
	v_exp_f32_e32 v56, v56
	v_exp_f32_e32 v57, v57
	s_waitcnt lgkmcnt(2)
	v_mfma_f32_32x32x16_bf16 v[18:33], v[146:149], v[70:73], v[18:33]
	v_exp_f32_e32 v58, v58
	v_exp_f32_e32 v59, v59
	v_exp_f32_e32 v60, v60
	v_exp_f32_e32 v61, v61
	s_waitcnt lgkmcnt(0)
	v_mfma_f32_32x32x16_bf16 v[34:49], v[146:149], v[74:77], v[34:49]
	v_exp_f32_e32 v62, v62
	v_exp_f32_e32 v63, v63
	v_exp_f32_e32 v64, v64
	v_exp_f32_e32 v65, v65
	v_add_f32_e32 v66, v82, v83
	v_add_f32_e32 v66, v84, v66
	v_add_f32_e32 v66, v85, v66
	v_add_f32_e32 v66, v86, v66
	v_add_f32_e32 v66, v87, v66
	v_add_f32_e32 v66, v88, v66
	v_add_f32_e32 v66, v89, v66
	v_add_f32_e32 v66, v90, v66
	v_add_f32_e32 v66, v91, v66
	v_add_f32_e32 v66, v92, v66
	v_add_f32_e32 v66, v93, v66
	v_add_f32_e32 v66, v94, v66
	v_add_f32_e32 v66, v95, v66
	v_add_f32_e32 v66, v96, v66
	v_add_f32_e32 v66, v97, v66
	v_add_f32_e32 v66, v50, v66
	v_add_f32_e32 v66, v51, v66
	v_add_f32_e32 v66, v52, v66
	v_add_f32_e32 v66, v53, v66
	v_add_f32_e32 v66, v54, v66
	v_add_f32_e32 v66, v55, v66
	v_add_f32_e32 v66, v56, v66
	v_add_f32_e32 v66, v57, v66
	v_add_f32_e32 v66, v58, v66
	v_add_f32_e32 v66, v59, v66
	v_add_f32_e32 v66, v60, v66
	v_add_f32_e32 v66, v61, v66
	v_add_f32_e32 v66, v62, v66
	v_add_f32_e32 v66, v63, v66
	v_add_f32_e32 v66, v64, v66
	v_add_f32_e32 v66, v65, v66
	v_add_f32_e32 v67, v118, v114
	v_add_f32_e32 v66, v67, v66
	v_cvt_pk_bf16_f32 v50, v50, v51
	v_cvt_pk_bf16_f32 v68, v82, v83
	v_cvt_pk_bf16_f32 v69, v84, v85
	v_cvt_pk_bf16_f32 v70, v86, v87
	v_cvt_pk_bf16_f32 v71, v88, v89
	v_cvt_pk_bf16_f32 v72, v90, v91
	v_cvt_pk_bf16_f32 v73, v92, v93
	v_cvt_pk_bf16_f32 v74, v94, v95
	v_cvt_pk_bf16_f32 v75, v96, v97
	v_cvt_pk_bf16_f32 v51, v52, v53
	v_cvt_pk_bf16_f32 v52, v54, v55
	v_cvt_pk_bf16_f32 v53, v56, v57
	v_cvt_pk_bf16_f32 v54, v58, v59
	v_cvt_pk_bf16_f32 v55, v60, v61
	v_cvt_pk_bf16_f32 v56, v62, v63
	v_cvt_pk_bf16_f32 v57, v64, v65
	ds_read_b64_tr_b16 v[58:59],v221 offset:0
	ds_read_b64_tr_b16 v[60:61],v221 offset:512
	ds_read_b64_tr_b16 v[62:63],v221 offset:1024
	ds_read_b64_tr_b16 v[64:65],v221 offset:1536
	ds_read_b64_tr_b16 v[76:77],v221 offset:2048
	ds_read_b64_tr_b16 v[78:79],v221 offset:2560
	ds_read_b64_tr_b16 v[80:81],v221 offset:3072
	ds_read_b64_tr_b16 v[82:83],v221 offset:3584
	s_waitcnt lgkmcnt(0)
	s_nop 0
	v_mfma_f32_32x32x16_bf16 v[18:33], v[68:71], v[58:61], v[18:33]
	ds_read_b64_tr_b16 v[58:59],v221 offset:4096
	ds_read_b64_tr_b16 v[60:61],v221 offset:4608
	v_mfma_f32_32x32x16_bf16 v[18:33], v[72:75], v[62:65], v[18:33]
	ds_read_b64_tr_b16 v[62:63],v221 offset:5120
	ds_read_b64_tr_b16 v[64:65],v221 offset:5632
	v_mfma_f32_32x32x16_bf16 v[18:33], v[50:53], v[76:79], v[18:33]
	ds_read_b64_tr_b16 v[76:77],v221 offset:6144
	ds_read_b64_tr_b16 v[78:79],v221 offset:6656
	v_mfma_f32_32x32x16_bf16 v[18:33], v[54:57], v[80:83], v[18:33]
	ds_read_b64_tr_b16 v[80:81],v221 offset:7168
	ds_read_b64_tr_b16 v[82:83],v221 offset:7680
	s_waitcnt lgkmcnt(0)
	v_mfma_f32_32x32x16_bf16 v[34:49], v[68:71], v[58:61], v[34:49]
	v_mfma_f32_32x32x16_bf16 v[34:49], v[72:75], v[62:65], v[34:49]
	v_mfma_f32_32x32x16_bf16 v[34:49], v[50:53], v[76:79], v[34:49]
	v_mov_b32_e32 v50, v66
	s_nop 1
	v_permlane32_swap_b32_e32 v66, v50
	v_mfma_f32_32x32x16_bf16 v[34:49], v[54:57], v[80:83], v[34:49]
	s_and_saveexec_b64 s[4:5], s[2:3]
	s_cbranch_execz .LBB0_823
	v_add_f32_e32 v50, v66, v50
	v_lshl_add_u32 v51, v1, 2, s0
	ds_write_b32 v51, v50 offset:49280
	s_branch .LBB0_823
